# convert phase: x f32->bf16 row loop software-pipelined (4 loads of next row in flight during processing of current row, counted vmcnt)
# baseline (speedup 1.0000x reference)
; __device__ __forceinline__ unsigned pk2(float lo, float hi) { const f32x2 v = {lo, hi}; const bf16x2_t b = __builtin_convertvector(v, bf16x2_t); return __builtin_bit_cast(unsigned, b); }
; __device__ __forceinline__ float wave_sum(float v) {
; #pragma unroll
;     for (int o = 1; o < 64; o <<= 1) v += __shfl_xor(v, o);
;     return v;
; __device__ __forceinline__ void phase_convert(int wid_s, KP p_, int l, float* ldsf, int bsub, int nb) {
;     ...
;     if (l == 0) {
;         const float* x = p->in[I_X]; bf16* xb = (bf16*)(ws + WS_XB); float* part = (float*)(ws + WS_PART);
;         for (int row = gw; row < T; row += NGW) {
;             const f32x4* xr = (const f32x4*)(x + (size_t)row * 1024) + lane; float s = 0.f;
; #pragma unroll
;             for (int j = 0; j < 4; ++j) { const f32x4 v = xr[64 * j]; s += (v.x * v.x + v.y * v.y) + (v.z * v.z + v.w * v.w);
;                 u32x2 w; w.x = pk2(v.x, v.y); w.y = pk2(v.z, v.w); *((u32x2*)(xb + (size_t)row * 1024) + lane + 64 * j) = w; }
;             s = wave_sum(s);
;             if (lane < 16) part[(size_t)row * 16 + lane] = lane == 0 ? s : 0.f;
;         }
.LBB0_417:
	s_or_b64 exec, exec, s[2:3]
	s_movk_i32 s2, 0x4000
	v_cmp_gt_i32_e32 vcc, s2, v78
	s_and_saveexec_b64 s[6:7], vcc
	s_cbranch_execz .LBB0_422
	v_and_b32_e32 v0, 64, v168
	v_add_u32_e32 v0, 64, v0
	v_xor_b32_e32 v1, 1, v168
	v_cmp_lt_i32_e32 vcc, v1, v0
	s_load_dwordx2 s[4:5], s[10:11], 0x0
	v_readlane_b32 s10, v254, 43
	v_cndmask_b32_e32 v1, v168, v1, vcc
	v_lshlrev_b32_e32 v6, 2, v1
	v_xor_b32_e32 v1, 2, v168
	v_cmp_lt_i32_e32 vcc, v1, v0
	v_ashrrev_i32_e32 v65, 31, v64
	v_readlane_b32 s11, v254, 44
	v_cndmask_b32_e32 v1, v168, v1, vcc
	v_lshlrev_b32_e32 v7, 2, v1
	v_xor_b32_e32 v1, 4, v168
	v_cmp_lt_i32_e32 vcc, v1, v0
	v_lshl_add_u64 v[4:5], s[10:11], 0, v[64:65]
	v_lshlrev_b64 v[2:3], 12, v[4:5]
	v_cndmask_b32_e32 v1, v168, v1, vcc
	v_lshlrev_b32_e32 v8, 2, v1
	v_xor_b32_e32 v1, 8, v168
	v_cmp_lt_i32_e32 vcc, v1, v0
	v_mov_b32_e32 v67, v145
	v_lshl_or_b32 v2, v79, 4, v2
	v_cndmask_b32_e32 v1, v168, v1, vcc
	v_lshlrev_b32_e32 v9, 2, v1
	v_xor_b32_e32 v1, 16, v168
	v_cmp_lt_i32_e32 vcc, v1, v0
	s_waitcnt lgkmcnt(0)
	v_lshl_add_u64 v[2:3], s[4:5], 0, v[2:3]
	s_mov_b64 s[4:5], 0xc00
	v_cndmask_b32_e32 v1, v168, v1, vcc
	v_lshlrev_b32_e32 v10, 2, v1
	v_xor_b32_e32 v1, 32, v168
	v_cmp_lt_i32_e32 vcc, v1, v0
	s_mov_b64 s[10:11], 0x4800000
	v_lshl_add_u64 v[2:3], v[2:3], 0, s[4:5]
	v_cndmask_b32_e32 v0, v168, v1, vcc
	v_lshlrev_b32_e32 v11, 2, v0
	v_lshlrev_b64 v[0:1], 6, v[4:5]
	v_lshlrev_b64 v[4:5], 11, v[4:5]
	v_lshl_add_u64 v[0:1], v[0:1], 0, v[66:67]
	v_lshl_or_b32 v4, v79, 3, v4
	v_lshl_add_u64 v[0:1], s[8:9], 0, v[0:1]
	v_lshl_add_u64 v[4:5], s[8:9], 0, v[4:5]
	s_mov_b64 s[4:5], 0x2800400
	v_cmp_gt_u32_e32 vcc, 16, v79
	v_cmp_eq_u32_e64 s[2:3], 0, v79
	v_lshl_add_u64 v[0:1], v[0:1], 0, s[10:11]
	v_lshl_add_u64 v[4:5], v[4:5], 0, s[4:5]
	s_mov_b64 s[8:9], 0
	global_load_dwordx4 v[36:39], v[2:3], off offset:-3072
	global_load_dwordx4 v[40:43], v[2:3], off offset:-2048
	global_load_dwordx4 v[44:47], v[2:3], off offset:-1024
	global_load_dwordx4 v[48:51], v[2:3], off
	s_waitcnt vmcnt(0)
	s_branch .LBB0_420

; __device__ __forceinline__ unsigned pk2(float lo, float hi) { const f32x2 v = {lo, hi}; const bf16x2_t b = __builtin_convertvector(v, bf16x2_t); return __builtin_bit_cast(unsigned, b); }
; __device__ __forceinline__ void phase_convert(int wid_s, KP p_, int l, float* ldsf, int bsub, int nb) {
;     ...
;     if (l == 0) {
;         const float* x = p->in[I_X]; bf16* xb = (bf16*)(ws + WS_XB); float* part = (float*)(ws + WS_PART);
;         for (int row = gw; row < T; row += NGW) {
;             const f32x4* xr = (const f32x4*)(x + (size_t)row * 1024) + lane; float s = 0.f;
; #pragma unroll
;             for (int j = 0; j < 4; ++j) { const f32x4 v = xr[64 * j]; s += (v.x * v.x + v.y * v.y) + (v.z * v.z + v.w * v.w);
;                 u32x2 w; w.x = pk2(v.x, v.y); w.y = pk2(v.z, v.w); *((u32x2*)(xb + (size_t)row * 1024) + lane + 64 * j) = w; }
;             s = wave_sum(s);
;             if (lane < 16) part[(size_t)row * 16 + lane] = lane == 0 ? s : 0.f;
;         }
.LBB0_420:
	s_waitcnt vmcnt(5) lgkmcnt(0)
	v_mov_b64_e32 v[12:13], v[36:37]
	v_mov_b64_e32 v[14:15], v[38:39]
	v_mov_b64_e32 v[16:17], v[40:41]
	v_mov_b64_e32 v[18:19], v[42:43]
	v_mov_b64_e32 v[20:21], v[44:45]
	v_mov_b64_e32 v[22:23], v[46:47]
	v_mov_b64_e32 v[24:25], v[48:49]
	v_mov_b64_e32 v[26:27], v[50:51]
	v_readfirstlane_b32 s4, v78
	s_add_i32 s4, s4, s52
	s_cmp_lt_i32 s4, 0x4000
	s_cbranch_scc0 .Lmy_cvx_nopf
	v_lshl_add_u64 v[52:53], v[2:3], 0, s[24:25]
	global_load_dwordx4 v[36:39], v[52:53], off offset:-3072
	global_load_dwordx4 v[40:43], v[52:53], off offset:-2048
	global_load_dwordx4 v[44:47], v[52:53], off offset:-1024
	global_load_dwordx4 v[48:51], v[52:53], off
.Lmy_cvx_nopf:
	v_cvt_pk_bf16_f32 v28, v12, v13
	v_cvt_pk_bf16_f32 v29, v14, v15
	global_store_dwordx2 v[4:5], v[28:29], off offset:-1024
	v_mul_f32_e32 v13, v13, v13
	v_mul_f32_e32 v15, v15, v15
	v_fmac_f32_e32 v13, v12, v12
	v_fmac_f32_e32 v15, v14, v14
	v_add_f32_e32 v12, v13, v15
	v_cvt_pk_bf16_f32 v30, v16, v17
	v_cvt_pk_bf16_f32 v31, v18, v19
	global_store_dwordx2 v[4:5], v[30:31], off offset:-512
	v_mul_f32_e32 v13, v17, v17
	v_mul_f32_e32 v14, v19, v19
	v_fmac_f32_e32 v13, v16, v16
	v_fmac_f32_e32 v14, v18, v18
	v_add_f32_e32 v13, v13, v14
	v_add_f32_e32 v12, v12, v13
	v_cvt_pk_bf16_f32 v32, v20, v21
	v_cvt_pk_bf16_f32 v33, v22, v23
	global_store_dwordx2 v[4:5], v[32:33], off
	v_mul_f32_e32 v13, v21, v21
	v_mul_f32_e32 v14, v23, v23
	v_fmac_f32_e32 v13, v20, v20
	v_fmac_f32_e32 v14, v22, v22
	v_add_f32_e32 v13, v13, v14
	v_add_f32_e32 v12, v12, v13
	v_mul_f32_e32 v13, v25, v25
	v_mul_f32_e32 v14, v27, v27
	v_fmac_f32_e32 v13, v24, v24
	v_fmac_f32_e32 v14, v26, v26
	v_add_f32_e32 v13, v13, v14
	v_add_f32_e32 v12, v12, v13
	ds_bpermute_b32 v13, v6, v12
	v_cvt_pk_bf16_f32 v34, v24, v25
	v_cvt_pk_bf16_f32 v35, v26, v27
	global_store_dwordx2 v[4:5], v[34:35], off offset:512
	s_waitcnt lgkmcnt(0)
	v_add_f32_e32 v12, v12, v13
	ds_bpermute_b32 v13, v7, v12
	s_waitcnt lgkmcnt(0)
	v_add_f32_e32 v12, v12, v13
	ds_bpermute_b32 v13, v8, v12
	s_waitcnt lgkmcnt(0)
	v_add_f32_e32 v12, v12, v13
	ds_bpermute_b32 v13, v9, v12
	s_waitcnt lgkmcnt(0)
	v_add_f32_e32 v12, v12, v13
	ds_bpermute_b32 v13, v10, v12
	s_waitcnt lgkmcnt(0)
	v_add_f32_e32 v12, v12, v13
	ds_bpermute_b32 v13, v11, v12
	s_and_saveexec_b64 s[4:5], vcc
	s_cbranch_execz .LBB0_419
	s_waitcnt lgkmcnt(0)
	v_add_f32_e32 v12, v12, v13
	v_cndmask_b32_e64 v12, 0, v12, s[2:3]
	global_store_dword v[0:1], v12, off
	s_branch .LBB0_419
